# P3 in-projection epilogue replaced by a lean lane-transposed path (bpermute, SGPR-base stores) for the 16 plain column tiles, plus SGPR-base LDS-DMA addressing in P1, P3, P9 K-loops
# speedup vs baseline: 1.0150x; 1.0086x over previous
;     __device__ __forceinline__ void operator()(Acc& acc, const Unit& u, int wr, int wc, int fr, int fq, const float (&rsa)[2][4]) const {
;         const int pn = u.pn;
;         bf16_t* dst; int ld = D, cbase; float scale = 1.f; int mode = 0;
;         if (pn < 4) { dst = QK; cbase = pn * BM; if (pn < 2) scale = 0.08838834764831845f; }
;         else if (pn < 8) { dst = V; cbase = (pn - 4) * BM; }
;         else if (pn < 12) { dst = SQ; cbase = (pn - 8) * BM; scale = 0.125f * LOG2E; }
;         else if (pn < 16) { dst = GR; cbase = (pn - 12) * BM; mode = 1; }
;         else if (pn == 16) { dst = SKVb; ld = 256; cbase = 0; mode = 2; }
;         else { dst = SKVb; cbase = 0; mode = 3; }
.LBB0_825:
	s_cmp_lt_u32 s34, 16
	s_cbranch_scc1 .Lp3_fast
	s_cmp_gt_i32 s34, 3
	s_mov_b64 s[70:71], -1
	s_cbranch_scc0 .LBB0_838
	s_cmp_gt_u32 s34, 7
	s_cbranch_scc0 .LBB0_835
	s_cmp_gt_u32 s34, 11
	s_cbranch_scc0 .LBB0_832
	s_cmp_gt_u32 s34, 15
	s_mov_b64 s[10:11], -1
	s_cbranch_scc0 .LBB0_830
	s_cmp_lg_u32 s34, 16
	s_cselect_b64 s[68:69], -1, 0
	s_cmp_eq_u32 s34, 16
	s_cselect_b64 s[62:63], -1, 0
	s_and_b64 s[10:11], s[62:63], exec
	s_movk_i32 s10, 0x400
	s_cselect_b32 s84, 0x100, s10
	s_mov_b64 s[10:11], 0
	s_mov_b64 s[64:65], s[84:85]

; __device__ __forceinline__ unsigned pk2(float lo, float hi) { f32x2_t v = {lo, hi}; bf16x2_t b = __builtin_convertvector(v, bf16x2_t); return __builtin_bit_cast(unsigned, b); }
; __device__ __forceinline__ float siluf_(float x) { return x * sigmoidf_(x); }
;     __device__ __forceinline__ void operator()(Acc& acc, const Unit& u, int wr, int wc, int fr, int fq, const float (&rsa)[2][4]) const {
;         const int pn = u.pn;
;         bf16_t* dst; int ld = D, cbase; float scale = 1.f; int mode = 0;
;         if (pn < 4) { dst = QK; cbase = pn * BM; if (pn < 2) scale = 0.08838834764831845f; }
;         else if (pn < 8) { dst = V; cbase = (pn - 4) * BM; }
;         else if (pn < 12) { dst = SQ; cbase = (pn - 8) * BM; scale = 0.125f * LOG2E; }
;         else if (pn < 16) { dst = GR; cbase = (pn - 12) * BM; mode = 1; }
;         else if (pn == 16) { dst = SKVb; ld = 256; cbase = 0; mode = 2; }
;         else { dst = SKVb; cbase = 0; mode = 3; }
; #pragma unroll
;         for (int ai = 0; ai < 2; ++ai)
; #pragma unroll
;             for (int m = 0; m < 4; ++m) {
;                 const int row = u.pm * BM + ai * HALF + wr * 64 + m * 16 + fr; const float rs = rsa[ai][m] * scale;
; #pragma unroll
;                 for (int bj = 0; bj < 2; ++bj) {
;                     const int within = bj * HALF + wc * 32 + 8 * fq;
;                     f32x4 v0 = acc[ai][bj][m][0] * rs, v1 = acc[ai][bj][m][1] * rs;
;                     if (mode == 3) { if (within < GRANK) { *(f32x4*)(GLR + (size_t)row * 16 + within) = v0; *(f32x4*)(GLR + (size_t)row * 16 + within + 4) = v1; } continue; }
;                     if (mode == 1) {
; #pragma unroll
;                         for (int j = 0; j < 4; ++j) { v0[j] = siluf_(v0[j]); v1[j] = siluf_(v1[j]); }
;                     }
;                     u32x4 w; w.x = pk2(v0[0], v0[1]); w.y = pk2(v0[2], v0[3]); w.z = pk2(v1[0], v1[1]); w.w = pk2(v1[2], v1[3]);
;                     *(u32x4*)(dst + (size_t)row * ld + cbase + within) = w;
.Lp3_fast:
	s_waitcnt lgkmcnt(0)
	v_readfirstlane_b32 s32, v0
	s_nop 3
	s_lshr_b32 s32, s32, 6
	s_lshr_b32 s79, s32, 2
	s_and_b32 s32, s32, 3
	s_lshl_b32 s86, s30, 8
	s_lshl_b32 s79, s79, 6
	s_add_u32 s86, s86, s79
	s_lshl_b32 s86, s86, 11
	s_and_b32 s79, s34, 3
	s_lshl_b32 s79, s79, 9
	s_lshl_b32 s32, s32, 6
	s_add_u32 s79, s79, s32
	s_add_u32 s86, s86, s79
	s_lshr_b32 s79, s34, 2
	s_mov_b32 s87, 0x7cc0000
	s_cmp_eq_u32 s79, 1
	s_cselect_b32 s87, 0xbd40000, s87
	s_cmp_eq_u32 s79, 2
	s_cselect_b32 s87, 0xfdc0000, s87
	s_cmp_eq_u32 s79, 3
	s_cselect_b32 s87, 0x17ec0000, s87
	s_add_u32 s86, s86, s87
	s_add_u32 s98, s96, s86
	s_addc_u32 s99, s97, 0
	s_mov_b32 s88, 1.0
	s_cmp_lt_u32 s34, 2
	s_cselect_b32 s88, 0x3db504f3, s88
	s_cmp_eq_u32 s79, 2
	s_cselect_b32 s88, 0x3e38aa3b, s88
	v_and_b32_e32 v222, 63, v0
	v_lshrrev_b32_e32 v223, 2, v222
	v_and_b32_e32 v222, 3, v222
	v_lshlrev_b32_e32 v220, 11, v223
	v_lshl_add_u32 v220, v222, 4, v220
	v_lshlrev_b32_e32 v221, 6, v222
	v_lshl_add_u32 v221, v223, 2, v221
	v_mul_f32_e32 v238, s88, v134
	v_pk_mul_f32 v[222:223], v[126:127], v[238:239] op_sel_hi:[1,0]
	v_pk_mul_f32 v[224:225], v[128:129], v[238:239] op_sel_hi:[1,0]
	v_pk_mul_f32 v[226:227], v[122:123], v[238:239] op_sel_hi:[1,0]
	v_pk_mul_f32 v[228:229], v[124:125], v[238:239] op_sel_hi:[1,0]
	s_cmp_lg_u32 s79, 3
	s_cbranch_scc1 .Lp3f_ns0
	v_mul_f32_e32 v230, 0xbfb8aa3b, v222
	v_mul_f32_e32 v231, 0xbfb8aa3b, v223
	v_mul_f32_e32 v232, 0xbfb8aa3b, v224
	v_mul_f32_e32 v233, 0xbfb8aa3b, v225
	v_mul_f32_e32 v234, 0xbfb8aa3b, v226
	v_mul_f32_e32 v235, 0xbfb8aa3b, v227
	v_mul_f32_e32 v236, 0xbfb8aa3b, v228
	v_mul_f32_e32 v237, 0xbfb8aa3b, v229
	v_exp_f32_e32 v230, v230
	v_exp_f32_e32 v231, v231
	v_exp_f32_e32 v232, v232
	v_exp_f32_e32 v233, v233
	v_exp_f32_e32 v234, v234
	v_exp_f32_e32 v235, v235
	v_exp_f32_e32 v236, v236
	v_exp_f32_e32 v237, v237
	v_add_f32_e32 v230, 1.0, v230
	v_add_f32_e32 v231, 1.0, v231
	v_add_f32_e32 v232, 1.0, v232
	v_add_f32_e32 v233, 1.0, v233
	v_add_f32_e32 v234, 1.0, v234
	v_add_f32_e32 v235, 1.0, v235
	v_add_f32_e32 v236, 1.0, v236
	v_add_f32_e32 v237, 1.0, v237
	v_rcp_f32_e32 v230, v230
	v_rcp_f32_e32 v231, v231
	v_rcp_f32_e32 v232, v232
	v_rcp_f32_e32 v233, v233
	v_rcp_f32_e32 v234, v234
	v_rcp_f32_e32 v235, v235
	v_rcp_f32_e32 v236, v236
	v_rcp_f32_e32 v237, v237
	v_pk_mul_f32 v[222:223], v[222:223], v[230:231]
	v_pk_mul_f32 v[224:225], v[224:225], v[232:233]
	v_pk_mul_f32 v[226:227], v[226:227], v[234:235]
	v_pk_mul_f32 v[228:229], v[228:229], v[236:237]
.Lp3f_ns0:
	v_cvt_pk_bf16_f32 v240, v222, v223
	v_cvt_pk_bf16_f32 v241, v224, v225
	v_cvt_pk_bf16_f32 v242, v226, v227
	v_cvt_pk_bf16_f32 v243, v228, v229
	ds_bpermute_b32 v244, v221, v240
	ds_bpermute_b32 v245, v221, v241
	ds_bpermute_b32 v246, v221, v242
	ds_bpermute_b32 v247, v221, v243
	v_pk_mul_f32 v[222:223], v[94:95], v[238:239] op_sel_hi:[1,0]
	v_pk_mul_f32 v[224:225], v[96:97], v[238:239] op_sel_hi:[1,0]
	v_pk_mul_f32 v[226:227], v[90:91], v[238:239] op_sel_hi:[1,0]
	v_pk_mul_f32 v[228:229], v[92:93], v[238:239] op_sel_hi:[1,0]
	s_cmp_lg_u32 s79, 3
	s_cbranch_scc1 .Lp3f_ns1
	v_mul_f32_e32 v230, 0xbfb8aa3b, v222
	v_mul_f32_e32 v231, 0xbfb8aa3b, v223
	v_mul_f32_e32 v232, 0xbfb8aa3b, v224
	v_mul_f32_e32 v233, 0xbfb8aa3b, v225
	v_mul_f32_e32 v234, 0xbfb8aa3b, v226
	v_mul_f32_e32 v235, 0xbfb8aa3b, v227
	v_mul_f32_e32 v236, 0xbfb8aa3b, v228
	v_mul_f32_e32 v237, 0xbfb8aa3b, v229
	v_exp_f32_e32 v230, v230
	v_exp_f32_e32 v231, v231
	v_exp_f32_e32 v232, v232
	v_exp_f32_e32 v233, v233
	v_exp_f32_e32 v234, v234
	v_exp_f32_e32 v235, v235
	v_exp_f32_e32 v236, v236
	v_exp_f32_e32 v237, v237
	v_add_f32_e32 v230, 1.0, v230
	v_add_f32_e32 v231, 1.0, v231
	v_add_f32_e32 v232, 1.0, v232
	v_add_f32_e32 v233, 1.0, v233
	v_add_f32_e32 v234, 1.0, v234
	v_add_f32_e32 v235, 1.0, v235
	v_add_f32_e32 v236, 1.0, v236
	v_add_f32_e32 v237, 1.0, v237
	v_rcp_f32_e32 v230, v230
	v_rcp_f32_e32 v231, v231
	v_rcp_f32_e32 v232, v232
	v_rcp_f32_e32 v233, v233
	v_rcp_f32_e32 v234, v234
	v_rcp_f32_e32 v235, v235
	v_rcp_f32_e32 v236, v236
	v_rcp_f32_e32 v237, v237
	v_pk_mul_f32 v[222:223], v[222:223], v[230:231]
	v_pk_mul_f32 v[224:225], v[224:225], v[232:233]
	v_pk_mul_f32 v[226:227], v[226:227], v[234:235]
	v_pk_mul_f32 v[228:229], v[228:229], v[236:237]
.Lp3f_ns1:
	v_cvt_pk_bf16_f32 v240, v222, v223
	v_cvt_pk_bf16_f32 v241, v224, v225
	v_cvt_pk_bf16_f32 v242, v226, v227
	v_cvt_pk_bf16_f32 v243, v228, v229
	ds_bpermute_b32 v248, v221, v240
	ds_bpermute_b32 v249, v221, v241
	ds_bpermute_b32 v250, v221, v242
	ds_bpermute_b32 v251, v221, v243
	s_waitcnt lgkmcnt(4)
	s_add_u32 s100, s98, 0x0
	s_addc_u32 s101, s99, 0
	global_store_dwordx4 v220, v[244:247], s[100:101] offset:0
	v_mul_f32_e32 v238, s88, v135
	v_pk_mul_f32 v[222:223], v[118:119], v[238:239] op_sel_hi:[1,0]
	v_pk_mul_f32 v[224:225], v[120:121], v[238:239] op_sel_hi:[1,0]
	v_pk_mul_f32 v[226:227], v[114:115], v[238:239] op_sel_hi:[1,0]
	v_pk_mul_f32 v[228:229], v[116:117], v[238:239] op_sel_hi:[1,0]
	s_cmp_lg_u32 s79, 3
	s_cbranch_scc1 .Lp3f_ns2
	v_mul_f32_e32 v230, 0xbfb8aa3b, v222
	v_mul_f32_e32 v231, 0xbfb8aa3b, v223
	v_mul_f32_e32 v232, 0xbfb8aa3b, v224
	v_mul_f32_e32 v233, 0xbfb8aa3b, v225
	v_mul_f32_e32 v234, 0xbfb8aa3b, v226
	v_mul_f32_e32 v235, 0xbfb8aa3b, v227
	v_mul_f32_e32 v236, 0xbfb8aa3b, v228
	v_mul_f32_e32 v237, 0xbfb8aa3b, v229
	v_exp_f32_e32 v230, v230
	v_exp_f32_e32 v231, v231
	v_exp_f32_e32 v232, v232
	v_exp_f32_e32 v233, v233
	v_exp_f32_e32 v234, v234
	v_exp_f32_e32 v235, v235
	v_exp_f32_e32 v236, v236
	v_exp_f32_e32 v237, v237
	v_add_f32_e32 v230, 1.0, v230
	v_add_f32_e32 v231, 1.0, v231
	v_add_f32_e32 v232, 1.0, v232
	v_add_f32_e32 v233, 1.0, v233
	v_add_f32_e32 v234, 1.0, v234
	v_add_f32_e32 v235, 1.0, v235
	v_add_f32_e32 v236, 1.0, v236
	v_add_f32_e32 v237, 1.0, v237
	v_rcp_f32_e32 v230, v230
	v_rcp_f32_e32 v231, v231
	v_rcp_f32_e32 v232, v232
	v_rcp_f32_e32 v233, v233
	v_rcp_f32_e32 v234, v234
	v_rcp_f32_e32 v235, v235
	v_rcp_f32_e32 v236, v236
	v_rcp_f32_e32 v237, v237
	v_pk_mul_f32 v[222:223], v[222:223], v[230:231]
	v_pk_mul_f32 v[224:225], v[224:225], v[232:233]
	v_pk_mul_f32 v[226:227], v[226:227], v[234:235]
	v_pk_mul_f32 v[228:229], v[228:229], v[236:237]
; __device__ __forceinline__ unsigned pk2(float lo, float hi) { f32x2_t v = {lo, hi}; bf16x2_t b = __builtin_convertvector(v, bf16x2_t); return __builtin_bit_cast(unsigned, b); }
; __device__ __forceinline__ float siluf_(float x) { return x * sigmoidf_(x); }
;     __device__ __forceinline__ void operator()(Acc& acc, const Unit& u, int wr, int wc, int fr, int fq, const float (&rsa)[2][4]) const {
;     ...
;                 const int row = u.pm * BM + ai * HALF + wr * 64 + m * 16 + fr; const float rs = rsa[ai][m] * scale;
; #pragma unroll
;                 for (int bj = 0; bj < 2; ++bj) {
;                     const int within = bj * HALF + wc * 32 + 8 * fq;
;                     f32x4 v0 = acc[ai][bj][m][0] * rs, v1 = acc[ai][bj][m][1] * rs;
;                     if (mode == 3) { if (within < GRANK) { *(f32x4*)(GLR + (size_t)row * 16 + within) = v0; *(f32x4*)(GLR + (size_t)row * 16 + within + 4) = v1; } continue; }
;                     if (mode == 1) {
; #pragma unroll
;                         for (int j = 0; j < 4; ++j) { v0[j] = siluf_(v0[j]); v1[j] = siluf_(v1[j]); }
;                     }
;                     u32x4 w; w.x = pk2(v0[0], v0[1]); w.y = pk2(v0[2], v0[3]); w.z = pk2(v1[0], v1[1]); w.w = pk2(v1[2], v1[3]);
;                     *(u32x4*)(dst + (size_t)row * ld + cbase + within) = w;
.Lp3f_ns2:
	v_cvt_pk_bf16_f32 v240, v222, v223
	v_cvt_pk_bf16_f32 v241, v224, v225
	v_cvt_pk_bf16_f32 v242, v226, v227
	v_cvt_pk_bf16_f32 v243, v228, v229
	ds_bpermute_b32 v244, v221, v240
	ds_bpermute_b32 v245, v221, v241
	ds_bpermute_b32 v246, v221, v242
	ds_bpermute_b32 v247, v221, v243
	s_waitcnt lgkmcnt(4)
	s_add_u32 s100, s98, 0x0
	s_addc_u32 s101, s99, 0
	global_store_dwordx4 v220, v[248:251], s[100:101] offset:256
	v_pk_mul_f32 v[222:223], v[86:87], v[238:239] op_sel_hi:[1,0]
	v_pk_mul_f32 v[224:225], v[88:89], v[238:239] op_sel_hi:[1,0]
	v_pk_mul_f32 v[226:227], v[82:83], v[238:239] op_sel_hi:[1,0]
	v_pk_mul_f32 v[228:229], v[84:85], v[238:239] op_sel_hi:[1,0]
	s_cmp_lg_u32 s79, 3
	s_cbranch_scc1 .Lp3f_ns3
	v_mul_f32_e32 v230, 0xbfb8aa3b, v222
	v_mul_f32_e32 v231, 0xbfb8aa3b, v223
	v_mul_f32_e32 v232, 0xbfb8aa3b, v224
	v_mul_f32_e32 v233, 0xbfb8aa3b, v225
	v_mul_f32_e32 v234, 0xbfb8aa3b, v226
	v_mul_f32_e32 v235, 0xbfb8aa3b, v227
	v_mul_f32_e32 v236, 0xbfb8aa3b, v228
	v_mul_f32_e32 v237, 0xbfb8aa3b, v229
	v_exp_f32_e32 v230, v230
	v_exp_f32_e32 v231, v231
	v_exp_f32_e32 v232, v232
	v_exp_f32_e32 v233, v233
	v_exp_f32_e32 v234, v234
	v_exp_f32_e32 v235, v235
	v_exp_f32_e32 v236, v236
	v_exp_f32_e32 v237, v237
	v_add_f32_e32 v230, 1.0, v230
	v_add_f32_e32 v231, 1.0, v231
	v_add_f32_e32 v232, 1.0, v232
	v_add_f32_e32 v233, 1.0, v233
	v_add_f32_e32 v234, 1.0, v234
	v_add_f32_e32 v235, 1.0, v235
	v_add_f32_e32 v236, 1.0, v236
	v_add_f32_e32 v237, 1.0, v237
	v_rcp_f32_e32 v230, v230
	v_rcp_f32_e32 v231, v231
	v_rcp_f32_e32 v232, v232
	v_rcp_f32_e32 v233, v233
	v_rcp_f32_e32 v234, v234
	v_rcp_f32_e32 v235, v235
	v_rcp_f32_e32 v236, v236
	v_rcp_f32_e32 v237, v237
	v_pk_mul_f32 v[222:223], v[222:223], v[230:231]
	v_pk_mul_f32 v[224:225], v[224:225], v[232:233]
	v_pk_mul_f32 v[226:227], v[226:227], v[234:235]
	v_pk_mul_f32 v[228:229], v[228:229], v[236:237]
.Lp3f_ns3:
	v_cvt_pk_bf16_f32 v240, v222, v223
	v_cvt_pk_bf16_f32 v241, v224, v225
	v_cvt_pk_bf16_f32 v242, v226, v227
	v_cvt_pk_bf16_f32 v243, v228, v229
	ds_bpermute_b32 v248, v221, v240
	ds_bpermute_b32 v249, v221, v241
	ds_bpermute_b32 v250, v221, v242
	ds_bpermute_b32 v251, v221, v243
	s_waitcnt lgkmcnt(4)
	s_add_u32 s100, s98, 0x8000
	s_addc_u32 s101, s99, 0
	global_store_dwordx4 v220, v[244:247], s[100:101] offset:0
	v_mul_f32_e32 v238, s88, v136
	v_pk_mul_f32 v[222:223], v[110:111], v[238:239] op_sel_hi:[1,0]
	v_pk_mul_f32 v[224:225], v[112:113], v[238:239] op_sel_hi:[1,0]
	v_pk_mul_f32 v[226:227], v[106:107], v[238:239] op_sel_hi:[1,0]
	v_pk_mul_f32 v[228:229], v[108:109], v[238:239] op_sel_hi:[1,0]
	s_cmp_lg_u32 s79, 3
	s_cbranch_scc1 .Lp3f_ns4
	v_mul_f32_e32 v230, 0xbfb8aa3b, v222
	v_mul_f32_e32 v231, 0xbfb8aa3b, v223
	v_mul_f32_e32 v232, 0xbfb8aa3b, v224
	v_mul_f32_e32 v233, 0xbfb8aa3b, v225
	v_mul_f32_e32 v234, 0xbfb8aa3b, v226
	v_mul_f32_e32 v235, 0xbfb8aa3b, v227
	v_mul_f32_e32 v236, 0xbfb8aa3b, v228
	v_mul_f32_e32 v237, 0xbfb8aa3b, v229
	v_exp_f32_e32 v230, v230
	v_exp_f32_e32 v231, v231
	v_exp_f32_e32 v232, v232
	v_exp_f32_e32 v233, v233
	v_exp_f32_e32 v234, v234
	v_exp_f32_e32 v235, v235
	v_exp_f32_e32 v236, v236
	v_exp_f32_e32 v237, v237
	v_add_f32_e32 v230, 1.0, v230
	v_add_f32_e32 v231, 1.0, v231
	v_add_f32_e32 v232, 1.0, v232
	v_add_f32_e32 v233, 1.0, v233
	v_add_f32_e32 v234, 1.0, v234
	v_add_f32_e32 v235, 1.0, v235
	v_add_f32_e32 v236, 1.0, v236
	v_add_f32_e32 v237, 1.0, v237
	v_rcp_f32_e32 v230, v230
	v_rcp_f32_e32 v231, v231
	v_rcp_f32_e32 v232, v232
	v_rcp_f32_e32 v233, v233
	v_rcp_f32_e32 v234, v234
	v_rcp_f32_e32 v235, v235
	v_rcp_f32_e32 v236, v236
	v_rcp_f32_e32 v237, v237
	v_pk_mul_f32 v[222:223], v[222:223], v[230:231]
	v_pk_mul_f32 v[224:225], v[224:225], v[232:233]
	v_pk_mul_f32 v[226:227], v[226:227], v[234:235]
	v_pk_mul_f32 v[228:229], v[228:229], v[236:237]
.Lp3f_ns4:
	v_cvt_pk_bf16_f32 v240, v222, v223
	v_cvt_pk_bf16_f32 v241, v224, v225
	v_cvt_pk_bf16_f32 v242, v226, v227
	v_cvt_pk_bf16_f32 v243, v228, v229
	ds_bpermute_b32 v244, v221, v240
	ds_bpermute_b32 v245, v221, v241
	ds_bpermute_b32 v246, v221, v242
	ds_bpermute_b32 v247, v221, v243
	s_waitcnt lgkmcnt(4)
	s_add_u32 s100, s98, 0x8000
	s_addc_u32 s101, s99, 0
	global_store_dwordx4 v220, v[248:251], s[100:101] offset:256
	v_pk_mul_f32 v[222:223], v[78:79], v[238:239] op_sel_hi:[1,0]
	v_pk_mul_f32 v[224:225], v[80:81], v[238:239] op_sel_hi:[1,0]
	v_pk_mul_f32 v[226:227], v[74:75], v[238:239] op_sel_hi:[1,0]
	v_pk_mul_f32 v[228:229], v[76:77], v[238:239] op_sel_hi:[1,0]
	s_cmp_lg_u32 s79, 3
	s_cbranch_scc1 .Lp3f_ns5
	v_mul_f32_e32 v230, 0xbfb8aa3b, v222
	v_mul_f32_e32 v231, 0xbfb8aa3b, v223
	v_mul_f32_e32 v232, 0xbfb8aa3b, v224
	v_mul_f32_e32 v233, 0xbfb8aa3b, v225
	v_mul_f32_e32 v234, 0xbfb8aa3b, v226
	v_mul_f32_e32 v235, 0xbfb8aa3b, v227
	v_mul_f32_e32 v236, 0xbfb8aa3b, v228
	v_mul_f32_e32 v237, 0xbfb8aa3b, v229
	v_exp_f32_e32 v230, v230
	v_exp_f32_e32 v231, v231
	v_exp_f32_e32 v232, v232
	v_exp_f32_e32 v233, v233
	v_exp_f32_e32 v234, v234
	v_exp_f32_e32 v235, v235
	v_exp_f32_e32 v236, v236
	v_exp_f32_e32 v237, v237
	v_add_f32_e32 v230, 1.0, v230
	v_add_f32_e32 v231, 1.0, v231
	v_add_f32_e32 v232, 1.0, v232
	v_add_f32_e32 v233, 1.0, v233
	v_add_f32_e32 v234, 1.0, v234
	v_add_f32_e32 v235, 1.0, v235
	v_add_f32_e32 v236, 1.0, v236
	v_add_f32_e32 v237, 1.0, v237
	v_rcp_f32_e32 v230, v230
	v_rcp_f32_e32 v231, v231
	v_rcp_f32_e32 v232, v232
	v_rcp_f32_e32 v233, v233
	v_rcp_f32_e32 v234, v234
	v_rcp_f32_e32 v235, v235
	v_rcp_f32_e32 v236, v236
	v_rcp_f32_e32 v237, v237
	v_pk_mul_f32 v[222:223], v[222:223], v[230:231]
	v_pk_mul_f32 v[224:225], v[224:225], v[232:233]
	v_pk_mul_f32 v[226:227], v[226:227], v[234:235]
	v_pk_mul_f32 v[228:229], v[228:229], v[236:237]
; __device__ __forceinline__ unsigned pk2(float lo, float hi) { f32x2_t v = {lo, hi}; bf16x2_t b = __builtin_convertvector(v, bf16x2_t); return __builtin_bit_cast(unsigned, b); }
; __device__ __forceinline__ float siluf_(float x) { return x * sigmoidf_(x); }
;     __device__ __forceinline__ void operator()(Acc& acc, const Unit& u, int wr, int wc, int fr, int fq, const float (&rsa)[2][4]) const {
;     ...
;                 const int row = u.pm * BM + ai * HALF + wr * 64 + m * 16 + fr; const float rs = rsa[ai][m] * scale;
; #pragma unroll
;                 for (int bj = 0; bj < 2; ++bj) {
;                     const int within = bj * HALF + wc * 32 + 8 * fq;
;                     f32x4 v0 = acc[ai][bj][m][0] * rs, v1 = acc[ai][bj][m][1] * rs;
;                     if (mode == 3) { if (within < GRANK) { *(f32x4*)(GLR + (size_t)row * 16 + within) = v0; *(f32x4*)(GLR + (size_t)row * 16 + within + 4) = v1; } continue; }
;                     if (mode == 1) {
; #pragma unroll
;                         for (int j = 0; j < 4; ++j) { v0[j] = siluf_(v0[j]); v1[j] = siluf_(v1[j]); }
;                     }
;                     u32x4 w; w.x = pk2(v0[0], v0[1]); w.y = pk2(v0[2], v0[3]); w.z = pk2(v1[0], v1[1]); w.w = pk2(v1[2], v1[3]);
;                     *(u32x4*)(dst + (size_t)row * ld + cbase + within) = w;
.Lp3f_ns5:
	v_cvt_pk_bf16_f32 v240, v222, v223
	v_cvt_pk_bf16_f32 v241, v224, v225
	v_cvt_pk_bf16_f32 v242, v226, v227
	v_cvt_pk_bf16_f32 v243, v228, v229
	ds_bpermute_b32 v248, v221, v240
	ds_bpermute_b32 v249, v221, v241
	ds_bpermute_b32 v250, v221, v242
	ds_bpermute_b32 v251, v221, v243
	s_waitcnt lgkmcnt(4)
	s_add_u32 s100, s98, 0x10000
	s_addc_u32 s101, s99, 0
	global_store_dwordx4 v220, v[244:247], s[100:101] offset:0
	v_mul_f32_e32 v238, s88, v137
	v_pk_mul_f32 v[222:223], v[102:103], v[238:239] op_sel_hi:[1,0]
	v_pk_mul_f32 v[224:225], v[104:105], v[238:239] op_sel_hi:[1,0]
	v_pk_mul_f32 v[226:227], v[98:99], v[238:239] op_sel_hi:[1,0]
	v_pk_mul_f32 v[228:229], v[100:101], v[238:239] op_sel_hi:[1,0]
	s_cmp_lg_u32 s79, 3
	s_cbranch_scc1 .Lp3f_ns6
	v_mul_f32_e32 v230, 0xbfb8aa3b, v222
	v_mul_f32_e32 v231, 0xbfb8aa3b, v223
	v_mul_f32_e32 v232, 0xbfb8aa3b, v224
	v_mul_f32_e32 v233, 0xbfb8aa3b, v225
	v_mul_f32_e32 v234, 0xbfb8aa3b, v226
	v_mul_f32_e32 v235, 0xbfb8aa3b, v227
	v_mul_f32_e32 v236, 0xbfb8aa3b, v228
	v_mul_f32_e32 v237, 0xbfb8aa3b, v229
	v_exp_f32_e32 v230, v230
	v_exp_f32_e32 v231, v231
	v_exp_f32_e32 v232, v232
	v_exp_f32_e32 v233, v233
	v_exp_f32_e32 v234, v234
	v_exp_f32_e32 v235, v235
	v_exp_f32_e32 v236, v236
	v_exp_f32_e32 v237, v237
	v_add_f32_e32 v230, 1.0, v230
	v_add_f32_e32 v231, 1.0, v231
	v_add_f32_e32 v232, 1.0, v232
	v_add_f32_e32 v233, 1.0, v233
	v_add_f32_e32 v234, 1.0, v234
	v_add_f32_e32 v235, 1.0, v235
	v_add_f32_e32 v236, 1.0, v236
	v_add_f32_e32 v237, 1.0, v237
	v_rcp_f32_e32 v230, v230
	v_rcp_f32_e32 v231, v231
	v_rcp_f32_e32 v232, v232
	v_rcp_f32_e32 v233, v233
	v_rcp_f32_e32 v234, v234
	v_rcp_f32_e32 v235, v235
	v_rcp_f32_e32 v236, v236
	v_rcp_f32_e32 v237, v237
	v_pk_mul_f32 v[222:223], v[222:223], v[230:231]
	v_pk_mul_f32 v[224:225], v[224:225], v[232:233]
	v_pk_mul_f32 v[226:227], v[226:227], v[234:235]
	v_pk_mul_f32 v[228:229], v[228:229], v[236:237]
.Lp3f_ns6:
	v_cvt_pk_bf16_f32 v240, v222, v223
	v_cvt_pk_bf16_f32 v241, v224, v225
	v_cvt_pk_bf16_f32 v242, v226, v227
	v_cvt_pk_bf16_f32 v243, v228, v229
	ds_bpermute_b32 v244, v221, v240
	ds_bpermute_b32 v245, v221, v241
	ds_bpermute_b32 v246, v221, v242
	ds_bpermute_b32 v247, v221, v243
	s_waitcnt lgkmcnt(4)
	s_add_u32 s100, s98, 0x10000
	s_addc_u32 s101, s99, 0
	global_store_dwordx4 v220, v[248:251], s[100:101] offset:256
	v_pk_mul_f32 v[222:223], v[70:71], v[238:239] op_sel_hi:[1,0]
	v_pk_mul_f32 v[224:225], v[72:73], v[238:239] op_sel_hi:[1,0]
	v_pk_mul_f32 v[226:227], v[66:67], v[238:239] op_sel_hi:[1,0]
	v_pk_mul_f32 v[228:229], v[68:69], v[238:239] op_sel_hi:[1,0]
	s_cmp_lg_u32 s79, 3
	s_cbranch_scc1 .Lp3f_ns7
	v_mul_f32_e32 v230, 0xbfb8aa3b, v222
	v_mul_f32_e32 v231, 0xbfb8aa3b, v223
	v_mul_f32_e32 v232, 0xbfb8aa3b, v224
	v_mul_f32_e32 v233, 0xbfb8aa3b, v225
	v_mul_f32_e32 v234, 0xbfb8aa3b, v226
	v_mul_f32_e32 v235, 0xbfb8aa3b, v227
	v_mul_f32_e32 v236, 0xbfb8aa3b, v228
	v_mul_f32_e32 v237, 0xbfb8aa3b, v229
	v_exp_f32_e32 v230, v230
	v_exp_f32_e32 v231, v231
	v_exp_f32_e32 v232, v232
	v_exp_f32_e32 v233, v233
	v_exp_f32_e32 v234, v234
	v_exp_f32_e32 v235, v235
	v_exp_f32_e32 v236, v236
	v_exp_f32_e32 v237, v237
	v_add_f32_e32 v230, 1.0, v230
	v_add_f32_e32 v231, 1.0, v231
	v_add_f32_e32 v232, 1.0, v232
	v_add_f32_e32 v233, 1.0, v233
	v_add_f32_e32 v234, 1.0, v234
	v_add_f32_e32 v235, 1.0, v235
	v_add_f32_e32 v236, 1.0, v236
	v_add_f32_e32 v237, 1.0, v237
	v_rcp_f32_e32 v230, v230
	v_rcp_f32_e32 v231, v231
	v_rcp_f32_e32 v232, v232
	v_rcp_f32_e32 v233, v233
	v_rcp_f32_e32 v234, v234
	v_rcp_f32_e32 v235, v235
	v_rcp_f32_e32 v236, v236
	v_rcp_f32_e32 v237, v237
	v_pk_mul_f32 v[222:223], v[222:223], v[230:231]
	v_pk_mul_f32 v[224:225], v[224:225], v[232:233]
	v_pk_mul_f32 v[226:227], v[226:227], v[234:235]
	v_pk_mul_f32 v[228:229], v[228:229], v[236:237]
.Lp3f_ns7:
	v_cvt_pk_bf16_f32 v240, v222, v223
	v_cvt_pk_bf16_f32 v241, v224, v225
	v_cvt_pk_bf16_f32 v242, v226, v227
	v_cvt_pk_bf16_f32 v243, v228, v229
	ds_bpermute_b32 v248, v221, v240
	ds_bpermute_b32 v249, v221, v241
	ds_bpermute_b32 v250, v221, v242
	ds_bpermute_b32 v251, v221, v243
	s_waitcnt lgkmcnt(4)
	s_add_u32 s100, s98, 0x18000
	s_addc_u32 s101, s99, 0
	global_store_dwordx4 v220, v[244:247], s[100:101] offset:0
	v_mul_f32_e32 v238, s88, v130
	v_pk_mul_f32 v[222:223], v[62:63], v[238:239] op_sel_hi:[1,0]
	v_pk_mul_f32 v[224:225], v[64:65], v[238:239] op_sel_hi:[1,0]
	v_pk_mul_f32 v[226:227], v[58:59], v[238:239] op_sel_hi:[1,0]
	v_pk_mul_f32 v[228:229], v[60:61], v[238:239] op_sel_hi:[1,0]
	s_cmp_lg_u32 s79, 3
	s_cbranch_scc1 .Lp3f_ns8
	v_mul_f32_e32 v230, 0xbfb8aa3b, v222
	v_mul_f32_e32 v231, 0xbfb8aa3b, v223
	v_mul_f32_e32 v232, 0xbfb8aa3b, v224
	v_mul_f32_e32 v233, 0xbfb8aa3b, v225
	v_mul_f32_e32 v234, 0xbfb8aa3b, v226
	v_mul_f32_e32 v235, 0xbfb8aa3b, v227
	v_mul_f32_e32 v236, 0xbfb8aa3b, v228
	v_mul_f32_e32 v237, 0xbfb8aa3b, v229
	v_exp_f32_e32 v230, v230
	v_exp_f32_e32 v231, v231
	v_exp_f32_e32 v232, v232
	v_exp_f32_e32 v233, v233
	v_exp_f32_e32 v234, v234
	v_exp_f32_e32 v235, v235
	v_exp_f32_e32 v236, v236
	v_exp_f32_e32 v237, v237
	v_add_f32_e32 v230, 1.0, v230
	v_add_f32_e32 v231, 1.0, v231
	v_add_f32_e32 v232, 1.0, v232
	v_add_f32_e32 v233, 1.0, v233
	v_add_f32_e32 v234, 1.0, v234
	v_add_f32_e32 v235, 1.0, v235
	v_add_f32_e32 v236, 1.0, v236
	v_add_f32_e32 v237, 1.0, v237
	v_rcp_f32_e32 v230, v230
	v_rcp_f32_e32 v231, v231
	v_rcp_f32_e32 v232, v232
	v_rcp_f32_e32 v233, v233
	v_rcp_f32_e32 v234, v234
	v_rcp_f32_e32 v235, v235
	v_rcp_f32_e32 v236, v236
	v_rcp_f32_e32 v237, v237
	v_pk_mul_f32 v[222:223], v[222:223], v[230:231]
	v_pk_mul_f32 v[224:225], v[224:225], v[232:233]
	v_pk_mul_f32 v[226:227], v[226:227], v[234:235]
	v_pk_mul_f32 v[228:229], v[228:229], v[236:237]
; __device__ __forceinline__ unsigned pk2(float lo, float hi) { f32x2_t v = {lo, hi}; bf16x2_t b = __builtin_convertvector(v, bf16x2_t); return __builtin_bit_cast(unsigned, b); }
; __device__ __forceinline__ float siluf_(float x) { return x * sigmoidf_(x); }
;     __device__ __forceinline__ void operator()(Acc& acc, const Unit& u, int wr, int wc, int fr, int fq, const float (&rsa)[2][4]) const {
;     ...
;                 const int row = u.pm * BM + ai * HALF + wr * 64 + m * 16 + fr; const float rs = rsa[ai][m] * scale;
; #pragma unroll
;                 for (int bj = 0; bj < 2; ++bj) {
;                     const int within = bj * HALF + wc * 32 + 8 * fq;
;                     f32x4 v0 = acc[ai][bj][m][0] * rs, v1 = acc[ai][bj][m][1] * rs;
;                     if (mode == 3) { if (within < GRANK) { *(f32x4*)(GLR + (size_t)row * 16 + within) = v0; *(f32x4*)(GLR + (size_t)row * 16 + within + 4) = v1; } continue; }
;                     if (mode == 1) {
; #pragma unroll
;                         for (int j = 0; j < 4; ++j) { v0[j] = siluf_(v0[j]); v1[j] = siluf_(v1[j]); }
;                     }
;                     u32x4 w; w.x = pk2(v0[0], v0[1]); w.y = pk2(v0[2], v0[3]); w.z = pk2(v1[0], v1[1]); w.w = pk2(v1[2], v1[3]);
;                     *(u32x4*)(dst + (size_t)row * ld + cbase + within) = w;
.Lp3f_ns8:
	v_cvt_pk_bf16_f32 v240, v222, v223
	v_cvt_pk_bf16_f32 v241, v224, v225
	v_cvt_pk_bf16_f32 v242, v226, v227
	v_cvt_pk_bf16_f32 v243, v228, v229
	ds_bpermute_b32 v244, v221, v240
	ds_bpermute_b32 v245, v221, v241
	ds_bpermute_b32 v246, v221, v242
	ds_bpermute_b32 v247, v221, v243
	s_waitcnt lgkmcnt(4)
	s_add_u32 s100, s98, 0x18000
	s_addc_u32 s101, s99, 0
	global_store_dwordx4 v220, v[248:251], s[100:101] offset:256
	v_pk_mul_f32 v[222:223], v[30:31], v[238:239] op_sel_hi:[1,0]
	v_pk_mul_f32 v[224:225], v[32:33], v[238:239] op_sel_hi:[1,0]
	v_pk_mul_f32 v[226:227], v[26:27], v[238:239] op_sel_hi:[1,0]
	v_pk_mul_f32 v[228:229], v[28:29], v[238:239] op_sel_hi:[1,0]
	s_cmp_lg_u32 s79, 3
	s_cbranch_scc1 .Lp3f_ns9
	v_mul_f32_e32 v230, 0xbfb8aa3b, v222
	v_mul_f32_e32 v231, 0xbfb8aa3b, v223
	v_mul_f32_e32 v232, 0xbfb8aa3b, v224
	v_mul_f32_e32 v233, 0xbfb8aa3b, v225
	v_mul_f32_e32 v234, 0xbfb8aa3b, v226
	v_mul_f32_e32 v235, 0xbfb8aa3b, v227
	v_mul_f32_e32 v236, 0xbfb8aa3b, v228
	v_mul_f32_e32 v237, 0xbfb8aa3b, v229
	v_exp_f32_e32 v230, v230
	v_exp_f32_e32 v231, v231
	v_exp_f32_e32 v232, v232
	v_exp_f32_e32 v233, v233
	v_exp_f32_e32 v234, v234
	v_exp_f32_e32 v235, v235
	v_exp_f32_e32 v236, v236
	v_exp_f32_e32 v237, v237
	v_add_f32_e32 v230, 1.0, v230
	v_add_f32_e32 v231, 1.0, v231
	v_add_f32_e32 v232, 1.0, v232
	v_add_f32_e32 v233, 1.0, v233
	v_add_f32_e32 v234, 1.0, v234
	v_add_f32_e32 v235, 1.0, v235
	v_add_f32_e32 v236, 1.0, v236
	v_add_f32_e32 v237, 1.0, v237
	v_rcp_f32_e32 v230, v230
	v_rcp_f32_e32 v231, v231
	v_rcp_f32_e32 v232, v232
	v_rcp_f32_e32 v233, v233
	v_rcp_f32_e32 v234, v234
	v_rcp_f32_e32 v235, v235
	v_rcp_f32_e32 v236, v236
	v_rcp_f32_e32 v237, v237
	v_pk_mul_f32 v[222:223], v[222:223], v[230:231]
	v_pk_mul_f32 v[224:225], v[224:225], v[232:233]
	v_pk_mul_f32 v[226:227], v[226:227], v[234:235]
	v_pk_mul_f32 v[228:229], v[228:229], v[236:237]
.Lp3f_ns9:
	v_cvt_pk_bf16_f32 v240, v222, v223
	v_cvt_pk_bf16_f32 v241, v224, v225
	v_cvt_pk_bf16_f32 v242, v226, v227
	v_cvt_pk_bf16_f32 v243, v228, v229
	ds_bpermute_b32 v248, v221, v240
	ds_bpermute_b32 v249, v221, v241
	ds_bpermute_b32 v250, v221, v242
	ds_bpermute_b32 v251, v221, v243
	s_waitcnt lgkmcnt(4)
	s_add_u32 s100, s98, 0x40000
	s_addc_u32 s101, s99, 0
	global_store_dwordx4 v220, v[244:247], s[100:101] offset:0
	v_mul_f32_e32 v238, s88, v131
	v_pk_mul_f32 v[222:223], v[54:55], v[238:239] op_sel_hi:[1,0]
	v_pk_mul_f32 v[224:225], v[56:57], v[238:239] op_sel_hi:[1,0]
	v_pk_mul_f32 v[226:227], v[50:51], v[238:239] op_sel_hi:[1,0]
	v_pk_mul_f32 v[228:229], v[52:53], v[238:239] op_sel_hi:[1,0]
	s_cmp_lg_u32 s79, 3
	s_cbranch_scc1 .Lp3f_ns10
	v_mul_f32_e32 v230, 0xbfb8aa3b, v222
	v_mul_f32_e32 v231, 0xbfb8aa3b, v223
	v_mul_f32_e32 v232, 0xbfb8aa3b, v224
	v_mul_f32_e32 v233, 0xbfb8aa3b, v225
	v_mul_f32_e32 v234, 0xbfb8aa3b, v226
	v_mul_f32_e32 v235, 0xbfb8aa3b, v227
	v_mul_f32_e32 v236, 0xbfb8aa3b, v228
	v_mul_f32_e32 v237, 0xbfb8aa3b, v229
	v_exp_f32_e32 v230, v230
	v_exp_f32_e32 v231, v231
	v_exp_f32_e32 v232, v232
	v_exp_f32_e32 v233, v233
	v_exp_f32_e32 v234, v234
	v_exp_f32_e32 v235, v235
	v_exp_f32_e32 v236, v236
	v_exp_f32_e32 v237, v237
	v_add_f32_e32 v230, 1.0, v230
	v_add_f32_e32 v231, 1.0, v231
	v_add_f32_e32 v232, 1.0, v232
	v_add_f32_e32 v233, 1.0, v233
	v_add_f32_e32 v234, 1.0, v234
	v_add_f32_e32 v235, 1.0, v235
	v_add_f32_e32 v236, 1.0, v236
	v_add_f32_e32 v237, 1.0, v237
	v_rcp_f32_e32 v230, v230
	v_rcp_f32_e32 v231, v231
	v_rcp_f32_e32 v232, v232
	v_rcp_f32_e32 v233, v233
	v_rcp_f32_e32 v234, v234
	v_rcp_f32_e32 v235, v235
	v_rcp_f32_e32 v236, v236
	v_rcp_f32_e32 v237, v237
	v_pk_mul_f32 v[222:223], v[222:223], v[230:231]
	v_pk_mul_f32 v[224:225], v[224:225], v[232:233]
	v_pk_mul_f32 v[226:227], v[226:227], v[234:235]
	v_pk_mul_f32 v[228:229], v[228:229], v[236:237]
.Lp3f_ns10:
	v_cvt_pk_bf16_f32 v240, v222, v223
	v_cvt_pk_bf16_f32 v241, v224, v225
	v_cvt_pk_bf16_f32 v242, v226, v227
	v_cvt_pk_bf16_f32 v243, v228, v229
	ds_bpermute_b32 v244, v221, v240
	ds_bpermute_b32 v245, v221, v241
	ds_bpermute_b32 v246, v221, v242
	ds_bpermute_b32 v247, v221, v243
	s_waitcnt lgkmcnt(4)
	s_add_u32 s100, s98, 0x40000
	s_addc_u32 s101, s99, 0
	global_store_dwordx4 v220, v[248:251], s[100:101] offset:256
	v_pk_mul_f32 v[222:223], v[22:23], v[238:239] op_sel_hi:[1,0]
	v_pk_mul_f32 v[224:225], v[24:25], v[238:239] op_sel_hi:[1,0]
	v_pk_mul_f32 v[226:227], v[18:19], v[238:239] op_sel_hi:[1,0]
	v_pk_mul_f32 v[228:229], v[20:21], v[238:239] op_sel_hi:[1,0]
	s_cmp_lg_u32 s79, 3
	s_cbranch_scc1 .Lp3f_ns11
	v_mul_f32_e32 v230, 0xbfb8aa3b, v222
	v_mul_f32_e32 v231, 0xbfb8aa3b, v223
	v_mul_f32_e32 v232, 0xbfb8aa3b, v224
	v_mul_f32_e32 v233, 0xbfb8aa3b, v225
	v_mul_f32_e32 v234, 0xbfb8aa3b, v226
	v_mul_f32_e32 v235, 0xbfb8aa3b, v227
	v_mul_f32_e32 v236, 0xbfb8aa3b, v228
	v_mul_f32_e32 v237, 0xbfb8aa3b, v229
	v_exp_f32_e32 v230, v230
	v_exp_f32_e32 v231, v231
	v_exp_f32_e32 v232, v232
	v_exp_f32_e32 v233, v233
	v_exp_f32_e32 v234, v234
	v_exp_f32_e32 v235, v235
	v_exp_f32_e32 v236, v236
	v_exp_f32_e32 v237, v237
	v_add_f32_e32 v230, 1.0, v230
	v_add_f32_e32 v231, 1.0, v231
	v_add_f32_e32 v232, 1.0, v232
	v_add_f32_e32 v233, 1.0, v233
	v_add_f32_e32 v234, 1.0, v234
	v_add_f32_e32 v235, 1.0, v235
	v_add_f32_e32 v236, 1.0, v236
	v_add_f32_e32 v237, 1.0, v237
	v_rcp_f32_e32 v230, v230
	v_rcp_f32_e32 v231, v231
	v_rcp_f32_e32 v232, v232
	v_rcp_f32_e32 v233, v233
	v_rcp_f32_e32 v234, v234
	v_rcp_f32_e32 v235, v235
	v_rcp_f32_e32 v236, v236
	v_rcp_f32_e32 v237, v237
	v_pk_mul_f32 v[222:223], v[222:223], v[230:231]
	v_pk_mul_f32 v[224:225], v[224:225], v[232:233]
	v_pk_mul_f32 v[226:227], v[226:227], v[234:235]
	v_pk_mul_f32 v[228:229], v[228:229], v[236:237]
; __device__ __forceinline__ unsigned pk2(float lo, float hi) { f32x2_t v = {lo, hi}; bf16x2_t b = __builtin_convertvector(v, bf16x2_t); return __builtin_bit_cast(unsigned, b); }
; __device__ __forceinline__ float siluf_(float x) { return x * sigmoidf_(x); }
;     __device__ __forceinline__ void operator()(Acc& acc, const Unit& u, int wr, int wc, int fr, int fq, const float (&rsa)[2][4]) const {
;     ...
;                 const int row = u.pm * BM + ai * HALF + wr * 64 + m * 16 + fr; const float rs = rsa[ai][m] * scale;
; #pragma unroll
;                 for (int bj = 0; bj < 2; ++bj) {
;                     const int within = bj * HALF + wc * 32 + 8 * fq;
;                     f32x4 v0 = acc[ai][bj][m][0] * rs, v1 = acc[ai][bj][m][1] * rs;
;                     if (mode == 3) { if (within < GRANK) { *(f32x4*)(GLR + (size_t)row * 16 + within) = v0; *(f32x4*)(GLR + (size_t)row * 16 + within + 4) = v1; } continue; }
;                     if (mode == 1) {
; #pragma unroll
;                         for (int j = 0; j < 4; ++j) { v0[j] = siluf_(v0[j]); v1[j] = siluf_(v1[j]); }
;                     }
;                     u32x4 w; w.x = pk2(v0[0], v0[1]); w.y = pk2(v0[2], v0[3]); w.z = pk2(v1[0], v1[1]); w.w = pk2(v1[2], v1[3]);
;                     *(u32x4*)(dst + (size_t)row * ld + cbase + within) = w;
.Lp3f_ns11:
	v_cvt_pk_bf16_f32 v240, v222, v223
	v_cvt_pk_bf16_f32 v241, v224, v225
	v_cvt_pk_bf16_f32 v242, v226, v227
	v_cvt_pk_bf16_f32 v243, v228, v229
	ds_bpermute_b32 v248, v221, v240
	ds_bpermute_b32 v249, v221, v241
	ds_bpermute_b32 v250, v221, v242
	ds_bpermute_b32 v251, v221, v243
	s_waitcnt lgkmcnt(4)
	s_add_u32 s100, s98, 0x48000
	s_addc_u32 s101, s99, 0
	global_store_dwordx4 v220, v[244:247], s[100:101] offset:0
	v_mul_f32_e32 v238, s88, v132
	v_pk_mul_f32 v[222:223], v[46:47], v[238:239] op_sel_hi:[1,0]
	v_pk_mul_f32 v[224:225], v[48:49], v[238:239] op_sel_hi:[1,0]
	v_pk_mul_f32 v[226:227], v[42:43], v[238:239] op_sel_hi:[1,0]
	v_pk_mul_f32 v[228:229], v[44:45], v[238:239] op_sel_hi:[1,0]
	s_cmp_lg_u32 s79, 3
	s_cbranch_scc1 .Lp3f_ns12
	v_mul_f32_e32 v230, 0xbfb8aa3b, v222
	v_mul_f32_e32 v231, 0xbfb8aa3b, v223
	v_mul_f32_e32 v232, 0xbfb8aa3b, v224
	v_mul_f32_e32 v233, 0xbfb8aa3b, v225
	v_mul_f32_e32 v234, 0xbfb8aa3b, v226
	v_mul_f32_e32 v235, 0xbfb8aa3b, v227
	v_mul_f32_e32 v236, 0xbfb8aa3b, v228
	v_mul_f32_e32 v237, 0xbfb8aa3b, v229
	v_exp_f32_e32 v230, v230
	v_exp_f32_e32 v231, v231
	v_exp_f32_e32 v232, v232
	v_exp_f32_e32 v233, v233
	v_exp_f32_e32 v234, v234
	v_exp_f32_e32 v235, v235
	v_exp_f32_e32 v236, v236
	v_exp_f32_e32 v237, v237
	v_add_f32_e32 v230, 1.0, v230
	v_add_f32_e32 v231, 1.0, v231
	v_add_f32_e32 v232, 1.0, v232
	v_add_f32_e32 v233, 1.0, v233
	v_add_f32_e32 v234, 1.0, v234
	v_add_f32_e32 v235, 1.0, v235
	v_add_f32_e32 v236, 1.0, v236
	v_add_f32_e32 v237, 1.0, v237
	v_rcp_f32_e32 v230, v230
	v_rcp_f32_e32 v231, v231
	v_rcp_f32_e32 v232, v232
	v_rcp_f32_e32 v233, v233
	v_rcp_f32_e32 v234, v234
	v_rcp_f32_e32 v235, v235
	v_rcp_f32_e32 v236, v236
	v_rcp_f32_e32 v237, v237
	v_pk_mul_f32 v[222:223], v[222:223], v[230:231]
	v_pk_mul_f32 v[224:225], v[224:225], v[232:233]
	v_pk_mul_f32 v[226:227], v[226:227], v[234:235]
	v_pk_mul_f32 v[228:229], v[228:229], v[236:237]
.Lp3f_ns12:
	v_cvt_pk_bf16_f32 v240, v222, v223
	v_cvt_pk_bf16_f32 v241, v224, v225
	v_cvt_pk_bf16_f32 v242, v226, v227
	v_cvt_pk_bf16_f32 v243, v228, v229
	ds_bpermute_b32 v244, v221, v240
	ds_bpermute_b32 v245, v221, v241
	ds_bpermute_b32 v246, v221, v242
	ds_bpermute_b32 v247, v221, v243
	s_waitcnt lgkmcnt(4)
	s_add_u32 s100, s98, 0x48000
	s_addc_u32 s101, s99, 0
	global_store_dwordx4 v220, v[248:251], s[100:101] offset:256
	v_pk_mul_f32 v[222:223], v[14:15], v[238:239] op_sel_hi:[1,0]
	v_pk_mul_f32 v[224:225], v[16:17], v[238:239] op_sel_hi:[1,0]
	v_pk_mul_f32 v[226:227], v[10:11], v[238:239] op_sel_hi:[1,0]
	v_pk_mul_f32 v[228:229], v[12:13], v[238:239] op_sel_hi:[1,0]
	s_cmp_lg_u32 s79, 3
	s_cbranch_scc1 .Lp3f_ns13
	v_mul_f32_e32 v230, 0xbfb8aa3b, v222
	v_mul_f32_e32 v231, 0xbfb8aa3b, v223
	v_mul_f32_e32 v232, 0xbfb8aa3b, v224
	v_mul_f32_e32 v233, 0xbfb8aa3b, v225
	v_mul_f32_e32 v234, 0xbfb8aa3b, v226
	v_mul_f32_e32 v235, 0xbfb8aa3b, v227
	v_mul_f32_e32 v236, 0xbfb8aa3b, v228
	v_mul_f32_e32 v237, 0xbfb8aa3b, v229
	v_exp_f32_e32 v230, v230
	v_exp_f32_e32 v231, v231
	v_exp_f32_e32 v232, v232
	v_exp_f32_e32 v233, v233
	v_exp_f32_e32 v234, v234
	v_exp_f32_e32 v235, v235
	v_exp_f32_e32 v236, v236
	v_exp_f32_e32 v237, v237
	v_add_f32_e32 v230, 1.0, v230
	v_add_f32_e32 v231, 1.0, v231
	v_add_f32_e32 v232, 1.0, v232
	v_add_f32_e32 v233, 1.0, v233
	v_add_f32_e32 v234, 1.0, v234
	v_add_f32_e32 v235, 1.0, v235
	v_add_f32_e32 v236, 1.0, v236
	v_add_f32_e32 v237, 1.0, v237
	v_rcp_f32_e32 v230, v230
	v_rcp_f32_e32 v231, v231
	v_rcp_f32_e32 v232, v232
	v_rcp_f32_e32 v233, v233
	v_rcp_f32_e32 v234, v234
	v_rcp_f32_e32 v235, v235
	v_rcp_f32_e32 v236, v236
	v_rcp_f32_e32 v237, v237
	v_pk_mul_f32 v[222:223], v[222:223], v[230:231]
	v_pk_mul_f32 v[224:225], v[224:225], v[232:233]
	v_pk_mul_f32 v[226:227], v[226:227], v[234:235]
	v_pk_mul_f32 v[228:229], v[228:229], v[236:237]
; __device__ __forceinline__ unsigned pk2(float lo, float hi) { f32x2_t v = {lo, hi}; bf16x2_t b = __builtin_convertvector(v, bf16x2_t); return __builtin_bit_cast(unsigned, b); }
; __device__ __forceinline__ float siluf_(float x) { return x * sigmoidf_(x); }
;     __device__ __forceinline__ void operator()(Acc& acc, const Unit& u, int wr, int wc, int fr, int fq, const float (&rsa)[2][4]) const {
;     ...
;                 const int row = u.pm * BM + ai * HALF + wr * 64 + m * 16 + fr; const float rs = rsa[ai][m] * scale;
; #pragma unroll
;                 for (int bj = 0; bj < 2; ++bj) {
;                     const int within = bj * HALF + wc * 32 + 8 * fq;
;                     f32x4 v0 = acc[ai][bj][m][0] * rs, v1 = acc[ai][bj][m][1] * rs;
;                     if (mode == 3) { if (within < GRANK) { *(f32x4*)(GLR + (size_t)row * 16 + within) = v0; *(f32x4*)(GLR + (size_t)row * 16 + within + 4) = v1; } continue; }
;                     if (mode == 1) {
; #pragma unroll
;                         for (int j = 0; j < 4; ++j) { v0[j] = siluf_(v0[j]); v1[j] = siluf_(v1[j]); }
;                     }
;                     u32x4 w; w.x = pk2(v0[0], v0[1]); w.y = pk2(v0[2], v0[3]); w.z = pk2(v1[0], v1[1]); w.w = pk2(v1[2], v1[3]);
;                     *(u32x4*)(dst + (size_t)row * ld + cbase + within) = w;
.Lp3f_ns13:
	v_cvt_pk_bf16_f32 v240, v222, v223
	v_cvt_pk_bf16_f32 v241, v224, v225
	v_cvt_pk_bf16_f32 v242, v226, v227
	v_cvt_pk_bf16_f32 v243, v228, v229
	ds_bpermute_b32 v248, v221, v240
	ds_bpermute_b32 v249, v221, v241
	ds_bpermute_b32 v250, v221, v242
	ds_bpermute_b32 v251, v221, v243
	s_waitcnt lgkmcnt(4)
	s_add_u32 s100, s98, 0x50000
	s_addc_u32 s101, s99, 0
	global_store_dwordx4 v220, v[244:247], s[100:101] offset:0
	v_mul_f32_e32 v238, s88, v133
	v_pk_mul_f32 v[222:223], v[38:39], v[238:239] op_sel_hi:[1,0]
	v_pk_mul_f32 v[224:225], v[40:41], v[238:239] op_sel_hi:[1,0]
	v_pk_mul_f32 v[226:227], v[34:35], v[238:239] op_sel_hi:[1,0]
	v_pk_mul_f32 v[228:229], v[36:37], v[238:239] op_sel_hi:[1,0]
	s_cmp_lg_u32 s79, 3
	s_cbranch_scc1 .Lp3f_ns14
	v_mul_f32_e32 v230, 0xbfb8aa3b, v222
	v_mul_f32_e32 v231, 0xbfb8aa3b, v223
	v_mul_f32_e32 v232, 0xbfb8aa3b, v224
	v_mul_f32_e32 v233, 0xbfb8aa3b, v225
	v_mul_f32_e32 v234, 0xbfb8aa3b, v226
	v_mul_f32_e32 v235, 0xbfb8aa3b, v227
	v_mul_f32_e32 v236, 0xbfb8aa3b, v228
	v_mul_f32_e32 v237, 0xbfb8aa3b, v229
	v_exp_f32_e32 v230, v230
	v_exp_f32_e32 v231, v231
	v_exp_f32_e32 v232, v232
	v_exp_f32_e32 v233, v233
	v_exp_f32_e32 v234, v234
	v_exp_f32_e32 v235, v235
	v_exp_f32_e32 v236, v236
	v_exp_f32_e32 v237, v237
	v_add_f32_e32 v230, 1.0, v230
	v_add_f32_e32 v231, 1.0, v231
	v_add_f32_e32 v232, 1.0, v232
	v_add_f32_e32 v233, 1.0, v233
	v_add_f32_e32 v234, 1.0, v234
	v_add_f32_e32 v235, 1.0, v235
	v_add_f32_e32 v236, 1.0, v236
	v_add_f32_e32 v237, 1.0, v237
	v_rcp_f32_e32 v230, v230
	v_rcp_f32_e32 v231, v231
	v_rcp_f32_e32 v232, v232
	v_rcp_f32_e32 v233, v233
	v_rcp_f32_e32 v234, v234
	v_rcp_f32_e32 v235, v235
	v_rcp_f32_e32 v236, v236
	v_rcp_f32_e32 v237, v237
	v_pk_mul_f32 v[222:223], v[222:223], v[230:231]
	v_pk_mul_f32 v[224:225], v[224:225], v[232:233]
	v_pk_mul_f32 v[226:227], v[226:227], v[234:235]
	v_pk_mul_f32 v[228:229], v[228:229], v[236:237]
.Lp3f_ns14:
	v_cvt_pk_bf16_f32 v240, v222, v223
	v_cvt_pk_bf16_f32 v241, v224, v225
	v_cvt_pk_bf16_f32 v242, v226, v227
	v_cvt_pk_bf16_f32 v243, v228, v229
	ds_bpermute_b32 v244, v221, v240
	ds_bpermute_b32 v245, v221, v241
	ds_bpermute_b32 v246, v221, v242
	ds_bpermute_b32 v247, v221, v243
	s_waitcnt lgkmcnt(4)
	s_add_u32 s100, s98, 0x50000
	s_addc_u32 s101, s99, 0
	global_store_dwordx4 v220, v[248:251], s[100:101] offset:256
	v_pk_mul_f32 v[222:223], v[6:7], v[238:239] op_sel_hi:[1,0]
	v_pk_mul_f32 v[224:225], v[8:9], v[238:239] op_sel_hi:[1,0]
	v_pk_mul_f32 v[226:227], v[2:3], v[238:239] op_sel_hi:[1,0]
	v_pk_mul_f32 v[228:229], v[4:5], v[238:239] op_sel_hi:[1,0]
	s_cmp_lg_u32 s79, 3
	s_cbranch_scc1 .Lp3f_ns15
	v_mul_f32_e32 v230, 0xbfb8aa3b, v222
	v_mul_f32_e32 v231, 0xbfb8aa3b, v223
	v_mul_f32_e32 v232, 0xbfb8aa3b, v224
	v_mul_f32_e32 v233, 0xbfb8aa3b, v225
	v_mul_f32_e32 v234, 0xbfb8aa3b, v226
	v_mul_f32_e32 v235, 0xbfb8aa3b, v227
	v_mul_f32_e32 v236, 0xbfb8aa3b, v228
	v_mul_f32_e32 v237, 0xbfb8aa3b, v229
	v_exp_f32_e32 v230, v230
	v_exp_f32_e32 v231, v231
	v_exp_f32_e32 v232, v232
	v_exp_f32_e32 v233, v233
	v_exp_f32_e32 v234, v234
	v_exp_f32_e32 v235, v235
	v_exp_f32_e32 v236, v236
	v_exp_f32_e32 v237, v237
	v_add_f32_e32 v230, 1.0, v230
	v_add_f32_e32 v231, 1.0, v231
	v_add_f32_e32 v232, 1.0, v232
	v_add_f32_e32 v233, 1.0, v233
	v_add_f32_e32 v234, 1.0, v234
	v_add_f32_e32 v235, 1.0, v235
	v_add_f32_e32 v236, 1.0, v236
	v_add_f32_e32 v237, 1.0, v237
	v_rcp_f32_e32 v230, v230
	v_rcp_f32_e32 v231, v231
	v_rcp_f32_e32 v232, v232
	v_rcp_f32_e32 v233, v233
	v_rcp_f32_e32 v234, v234
	v_rcp_f32_e32 v235, v235
	v_rcp_f32_e32 v236, v236
	v_rcp_f32_e32 v237, v237
	v_pk_mul_f32 v[222:223], v[222:223], v[230:231]
	v_pk_mul_f32 v[224:225], v[224:225], v[232:233]
	v_pk_mul_f32 v[226:227], v[226:227], v[234:235]
	v_pk_mul_f32 v[228:229], v[228:229], v[236:237]
.Lp3f_ns15:
	v_cvt_pk_bf16_f32 v240, v222, v223
	v_cvt_pk_bf16_f32 v241, v224, v225
	v_cvt_pk_bf16_f32 v242, v226, v227
	v_cvt_pk_bf16_f32 v243, v228, v229
	ds_bpermute_b32 v248, v221, v240
	ds_bpermute_b32 v249, v221, v241
	ds_bpermute_b32 v250, v221, v242
	ds_bpermute_b32 v251, v221, v243
	s_waitcnt lgkmcnt(4)
	s_add_u32 s100, s98, 0x58000
	s_addc_u32 s101, s99, 0
	global_store_dwordx4 v220, v[244:247], s[100:101] offset:0
	s_waitcnt lgkmcnt(0)
	s_add_u32 s100, s98, 0x58000
	s_addc_u32 s101, s99, 0
	global_store_dwordx4 v220, v[248:251], s[100:101] offset:256
	s_branch .LBB0_992
